# stack of small exact edits on top: queue ticket prefetch, packed subtract in diff path, s_nop pads removed in dilated loops
# baseline (speedup 1.0000x reference)
; DI int tidx() { int t = __builtin_amdgcn_workitem_id_x(); asm volatile("" : "+v"(t)); return t; }
; DI void run_phase(const Params& p, int ph, char* lds, int bid, int nb) {
;     ...
;     int* su = (int*)(lds + LDS_BYTES - 16);
;     for (;;) {
;       __syncthreads();
;       if (tidx() == 0) *su = (int)atomicAdd(p.nmax + 6144 + l, 1u);
;       __syncthreads();
;       const int q = *su;
.LBB0_573:
	s_or_b64 exec, exec, s[0:1]
	v_readlane_b32 s0, v252, 0
	v_readlane_b32 s2, v252, 2
	v_readlane_b32 s4, v252, 4
	v_readlane_b32 s3, v252, 3
	v_readlane_b32 s5, v252, 5
	s_add_u32 s2, s4, 0x6000
	s_addc_u32 s3, s5, 0
	v_readlane_b32 s6, v252, 6
	v_readlane_b32 s7, v252, 7
	v_readlane_b32 s8, v252, 8
	v_readlane_b32 s9, v252, 9
	v_readlane_b32 s10, v252, 10
	v_readlane_b32 s11, v252, 11
	s_add_u32 s0, s4, 0x4000
	v_writelane_b32 v253, s0, 23
	s_addc_u32 s0, s5, 0
	v_readlane_b32 s4, v252, 36
	v_readlane_b32 s6, v252, 38
	v_writelane_b32 v253, s0, 25
	v_readlane_b32 s7, v252, 39
	s_add_u32 s0, s6, 0x100
	v_writelane_b32 v254, s0, 63
	s_addc_u32 s0, s7, 0
	s_waitcnt lgkmcnt(0)
	v_mbcnt_lo_u32_b32 v0, -1, 0
	v_readlane_b32 s12, v252, 12
	v_readlane_b32 s13, v252, 13
	v_readlane_b32 s14, v252, 14
	v_readlane_b32 s15, v252, 15
	v_readlane_b32 s5, v252, 37
	v_readlane_b32 s10, v252, 42
	v_readlane_b32 s11, v252, 43
	v_writelane_b32 v255, s0, 0
	s_add_u32 s0, s4, 0x100
	v_mbcnt_hi_u32_b32 v207, -1, v0
	v_readlane_b32 s8, v252, 40
	v_readlane_b32 s9, v252, 41
	v_writelane_b32 v255, s0, 1
	s_addc_u32 s0, s5, 0
	s_mov_b32 s6, 0x41000000
	s_mov_b32 s10, 0x3f828f5c
	s_mov_b32 s12, 2.0
	s_mov_b32 s14, 0x41200000
	s_mov_b32 s34, 0x41800000
	s_mov_b32 s44, 0x41900000
	s_mov_b32 s46, 0x41c00000
	s_mov_b32 s48, 0x41d00000
	s_mov_b32 s16, 0x42280000
	s_mov_b32 s18, 0x42200000
	s_mov_b32 s20, 0x42080000
	s_mov_b32 s22, 0x42000000
	v_and_b32_e32 v0, 64, v207
	v_writelane_b32 v255, s0, 2
	s_mov_b32 s5, 0
	v_mov_b32_e32 v113, 0
	v_mov_b32_e32 v166, 0x1fff0
	s_movk_i32 s72, 0x1600
	s_movk_i32 s73, 0x90
	s_mov_b32 s7, 0x41100000
	s_mov_b64 s[8:9], 0x80
	s_movk_i32 s74, 0x1000
	s_mov_b32 s75, 0xf800000
	v_mov_b32_e32 v167, 0x260
	s_mov_b32 s11, 0x3fb8aa3b
	s_mov_b32 s24, 0xc2200000
	s_mov_b32 s13, 0x40400000
	s_mov_b32 s15, 0x41300000
	s_mov_b32 s35, 0x41880000
	s_mov_b32 s45, 0x41980000
	s_mov_b32 s47, 0x41c80000
	s_mov_b32 s49, 0x41d80000
	s_mov_b32 s17, 0x422c0000
	s_mov_b32 s19, 0x42240000
	s_mov_b32 s21, 0x420c0000
	s_mov_b32 s23, 0x42040000
	v_mov_b32_e32 v115, 0x41000000
	s_mov_b32 s25, 0xc2ce8ed0
	s_mov_b32 s26, 0x42b17218
	v_mov_b32_e32 v168, 0x358637bd
	s_mov_b32 s27, 0x80000
	s_mov_b32 s28, 0x100000
	s_mov_b32 s29, 0xc2fc0000
	s_mov_b32 s30, 0x1000000
	s_brev_b32 s31, 64
	v_xor_b32_e32 v209, 32, v207
	v_add_u32_e32 v208, 64, v0
	v_mov_b32_e32 v169, 0x42800000
	v_mov_b32_e32 v170, 0x7f800000
	v_not_b32_e32 v171, 63
	s_barrier
	v_cmp_eq_u32_e32 vcc, 0, v206
	s_and_saveexec_b64 s[66:67], vcc
	v_mov_b32_e32 v244, 1
	global_atomic_add v245, v113, v244, s[2:3] sc0
	s_or_b64 exec, exec, s[66:67]
	v_readlane_b32 s1, v252, 1
	s_branch .LBB0_576

; DI int tidx() { int t = __builtin_amdgcn_workitem_id_x(); asm volatile("" : "+v"(t)); return t; }
; DI void run_phase(const Params& p, int ph, char* lds, int bid, int nb) {
;     ...
;       __syncthreads();
;       if (tidx() == 0) *su = (int)atomicAdd(p.nmax + 6144 + l, 1u);
;       __syncthreads();
;       const int q = *su;
.LBB0_576:
	v_mov_b32_e32 v0, v206
	s_barrier
	s_nop 0
	v_cmp_eq_u32_e32 vcc, 0, v0
	s_and_saveexec_b64 s[0:1], vcc
	s_cbranch_execz .LBB0_580
	s_mov_b64 s[68:69], exec
	v_mbcnt_lo_u32_b32 v0, s68, 0
	v_mbcnt_hi_u32_b32 v0, s69, v0
	v_cmp_eq_u32_e32 vcc, 0, v0
	s_and_saveexec_b64 s[66:67], vcc
	s_cbranch_execz .LBB0_579
	s_bcnt1_i32_b64 s4, s[68:69]
	s_waitcnt vmcnt(0)
	v_mov_b32_e32 v1, v245
	v_mov_b32_e32 v244, s4
	global_atomic_add v245, v113, v244, s[2:3] sc0
.LBB0_579:
	s_or_b64 exec, exec, s[66:67]
	v_readfirstlane_b32 s4, v1
	s_nop 1
	v_add_u32_e32 v0, s4, v0
	ds_write_b32 v166, v0

; DI int tidx() { int t = __builtin_amdgcn_workitem_id_x(); asm volatile("" : "+v"(t)); return t; }
; DI void run_phase(const Params& p, int ph, char* lds, int bid, int nb) {
;     ...
;     int* su = (int*)(lds + LDS_BYTES - 16);
;     for (;;) {
;       __syncthreads();
;       if (tidx() == 0) *su = (int)atomicAdd(p.nmax + 6144 + l, 1u);
;       __syncthreads();
;       const int q = *su;
.LBB0_1550:
	s_or_b64 exec, exec, s[0:1]
	v_readlane_b32 s0, v252, 0
	v_readlane_b32 s2, v252, 2
	v_readlane_b32 s4, v252, 4
	v_readlane_b32 s6, v252, 6
	v_readlane_b32 s7, v252, 7
	v_readlane_b32 s3, v252, 3
	v_readlane_b32 s5, v252, 5
	s_add_u32 s2, s4, 0x6004
	s_mov_b32 s6, 0x41000000
	s_mov_b32 s28, 0x3f828f5c
	s_mov_b32 s30, 2.0
	s_mov_b32 s36, 0x41200000
	s_mov_b32 s34, 0x41800000
	s_mov_b32 s44, 0x41900000
	s_mov_b32 s46, 0x41c00000
	s_mov_b32 s48, 0x41d00000
	s_mov_b32 s86, 0x42680000
	s_mov_b32 s92, 0x42600000
	s_mov_b32 s38, 0x42400000
	s_mov_b32 s40, 0x42280000
	s_mov_b32 s42, 0x42200000
	s_mov_b32 s84, 0x42080000
	s_mov_b32 s24, 0x42000000
	s_addc_u32 s3, s5, 0
	s_mov_b32 s5, 0
	v_mov_b32_e32 v113, 0
	v_mov_b32_e32 v166, 0x1fff0
	s_movk_i32 s72, 0x1600
	s_movk_i32 s73, 0x90
	s_mov_b32 s7, 0x41100000
	s_mov_b64 s[26:27], 0x80
	s_movk_i32 s74, 0x1000
	s_mov_b32 s75, 0xf800000
	v_mov_b32_e32 v167, 0x260
	s_mov_b32 s29, 0x3fb8aa3b
	s_mov_b32 s76, 0xc2200000
	s_mov_b32 s31, 0x40400000
	s_mov_b32 s37, 0x41300000
	s_mov_b32 s35, 0x41880000
	s_mov_b32 s45, 0x41980000
	s_mov_b32 s47, 0x41c80000
	s_mov_b32 s49, 0x41d80000
	s_mov_b32 s87, 0x426c0000
	s_mov_b32 s93, 0x42640000
	s_mov_b32 s39, 0x42440000
	s_mov_b32 s41, 0x422c0000
	s_mov_b32 s43, 0x42240000
	s_mov_b32 s85, 0x420c0000
	s_mov_b32 s25, 0x42040000
	v_mov_b32_e32 v115, 0x41000000
	s_mov_b32 s77, 0xc2ce8ed0
	s_mov_b32 s78, 0x42b17218
	v_mov_b32_e32 v168, 0x358637bd
	s_mov_b32 s79, 0x80000
	s_mov_b32 s80, 0x100000
	s_mov_b32 s81, 0xc2fc0000
	s_mov_b32 s82, 0x1000000
	s_brev_b32 s83, 64
	v_mov_b32_e32 v169, 0x42800000
	v_mov_b32_e32 v170, 0x7f800000
	v_not_b32_e32 v171, 63
	s_waitcnt lgkmcnt(0)
	s_barrier
	v_cmp_eq_u32_e32 vcc, 0, v206
	s_and_saveexec_b64 s[66:67], vcc
	v_mov_b32_e32 v244, 1
	global_atomic_add v245, v113, v244, s[2:3] sc0
	s_or_b64 exec, exec, s[66:67]
	v_readlane_b32 s1, v252, 1
	v_readlane_b32 s8, v252, 8
	v_readlane_b32 s9, v252, 9
	v_readlane_b32 s10, v252, 10
	v_readlane_b32 s11, v252, 11
	v_readlane_b32 s12, v252, 12
	v_readlane_b32 s13, v252, 13
	v_readlane_b32 s14, v252, 14
	v_readlane_b32 s15, v252, 15
	s_branch .LBB0_1553
